# accumulator zeroing before 4 GEMM K-loops paired into v_mov_b64 (252 fewer VALU instrs per unit set), on top of static first-half priority
# speedup vs baseline: 1.0070x; 1.0015x over previous
; template <class Epi, bool ALIGN_EPI = true, bool SP2 = true>
; __device__ __forceinline__ void gemm_phase(LAS unsigned char* lds, const Gemm g, const Order& S, const Epi& E) {
;     ...
;         const bool has_next = S.next(ui + 1, nxt);
;         const char* nA = has_next ? (const char*)(nxt.z ? g.A1 : g.A0) + (size_t)nxt.pm * tstepA + (size_t)nxt.kt0 * kstep : cA; const char* nB = has_next ? (const char*)(nxt.z ? g.B1 : g.B0) + (size_t)nxt.pn * tstepB + (size_t)nxt.kt0 * kstep : cB;
;         const int nt = cur.nkt;
;     ...
;         for (int a = 0; a < 2; ++a)
; #pragma unroll
;             for (int b = 0; b < 2; ++b)
; #pragma unroll
;                 for (int m = 0; m < 4; ++m)
; #pragma unroll
;                     for (int n = 0; n < 2; ++n) acc[a][b][m][n] = (f32x4){0.f, 0.f, 0.f, 0.f};
.LBB0_160:
	s_ashr_i32 s89, s88, 31
	s_lshl_b64 s[50:51], s[88:89], 19
	s_add_u32 s52, s23, s50
	s_addc_u32 s53, s24, s51
	s_and_b64 s[50:51], s[92:93], exec
	s_cselect_b32 s91, s53, s13
	s_cselect_b32 s90, s52, s12
	s_ashr_i32 s87, s86, 31
	s_lshl_b64 s[50:51], s[86:87], 19
	s_add_u32 s52, s60, s50
	s_addc_u32 s53, s61, s51
	s_and_b64 s[50:51], s[92:93], exec
	s_cselect_b32 s93, s53, s15
	s_cselect_b32 s92, s52, s14
	s_add_u32 s12, s12, 0x40080
	s_addc_u32 s13, s13, 0
	s_add_u32 s50, s14, 0x100
	v_mov_b32_e32 v2, 0
	s_addc_u32 s51, s15, 0
	s_mov_b32 s52, -2
	v_mov_b32_e32 v3, v2
	v_mov_b64_e32 v[4:5], 0
	v_mov_b64_e32 v[6:7], 0
	v_mov_b64_e32 v[8:9], 0
	v_mov_b64_e32 v[14:15], 0
	v_mov_b64_e32 v[16:17], 0
	v_mov_b64_e32 v[22:23], 0
	v_mov_b64_e32 v[24:25], 0
	v_mov_b64_e32 v[30:31], 0
	v_mov_b64_e32 v[32:33], 0
	v_mov_b64_e32 v[38:39], 0
	v_mov_b64_e32 v[40:41], 0
	v_mov_b64_e32 v[46:47], 0
	v_mov_b64_e32 v[48:49], 0
	v_mov_b64_e32 v[54:55], 0
	v_mov_b64_e32 v[56:57], 0
	v_mov_b64_e32 v[10:11], 0
	v_mov_b64_e32 v[12:13], 0
	v_mov_b64_e32 v[18:19], 0
	v_mov_b64_e32 v[20:21], 0
	v_mov_b64_e32 v[26:27], 0
	v_mov_b64_e32 v[28:29], 0
	v_mov_b64_e32 v[34:35], 0
	v_mov_b64_e32 v[36:37], 0
	v_mov_b64_e32 v[42:43], 0
	v_mov_b64_e32 v[44:45], 0
	v_mov_b64_e32 v[50:51], 0
	v_mov_b64_e32 v[52:53], 0
	v_mov_b64_e32 v[58:59], 0
	v_mov_b64_e32 v[60:61], 0
	v_mov_b64_e32 v[62:63], 0
	v_mov_b64_e32 v[64:65], 0
	v_mov_b64_e32 v[66:67], 0
	v_mov_b64_e32 v[68:69], 0
	v_mov_b64_e32 v[70:71], 0
	v_mov_b64_e32 v[72:73], 0
	v_mov_b64_e32 v[82:83], 0
	v_mov_b64_e32 v[84:85], 0
	v_mov_b64_e32 v[86:87], 0
	v_mov_b64_e32 v[88:89], 0
	v_mov_b64_e32 v[98:99], 0
	v_mov_b64_e32 v[100:101], 0
	v_mov_b64_e32 v[102:103], 0
	v_mov_b64_e32 v[104:105], 0
	v_mov_b64_e32 v[114:115], 0
	v_mov_b64_e32 v[116:117], 0
	v_mov_b64_e32 v[118:119], 0
	v_mov_b64_e32 v[120:121], 0
	v_mov_b64_e32 v[74:75], 0
	v_mov_b64_e32 v[76:77], 0
	v_mov_b64_e32 v[78:79], 0
	v_mov_b64_e32 v[80:81], 0
	v_mov_b64_e32 v[90:91], 0
	v_mov_b64_e32 v[92:93], 0
	v_mov_b64_e32 v[94:95], 0
	v_mov_b64_e32 v[96:97], 0
	v_mov_b64_e32 v[106:107], 0
	v_mov_b64_e32 v[108:109], 0
	v_mov_b64_e32 v[110:111], 0
	v_mov_b64_e32 v[112:113], 0
	v_mov_b64_e32 v[122:123], 0
	v_mov_b64_e32 v[124:125], 0
	v_mov_b64_e32 v[126:127], 0
	v_mov_b64_e32 v[128:129], 0
	s_cmp_lg_u32 s80, 0
	s_cbranch_scc0 .Lsprio_skip_0
	s_setprio 1

; template <class Epi, bool ALIGN_EPI = true, bool SP2 = true>
; __device__ __forceinline__ void gemm_phase(LAS unsigned char* lds, const Gemm g, const Order& S, const Epi& E) {
;     ...
;         const int nt = cur.nkt;
;         for (int t = 0; t < nt; t += 2) {
;             const bool last = (t == nt - 2);
;     ...
;         for (int a = 0; a < 2; ++a)
; #pragma unroll
;             for (int b = 0; b < 2; ++b)
; #pragma unroll
;                 for (int m = 0; m < 4; ++m)
; #pragma unroll
;                     for (int n = 0; n < 2; ++n) acc[a][b][m][n] = (f32x4){0.f, 0.f, 0.f, 0.f};
.LBB0_723:
	s_add_i32 s13, s54, -2
	s_add_u32 s15, s68, 0x100
	v_mov_b32_e32 v2, 0
	s_addc_u32 s55, s69, 0
	s_mov_b32 s57, 0
	v_mov_b32_e32 v3, v2
	v_mov_b64_e32 v[4:5], 0
	v_mov_b64_e32 v[6:7], 0
	v_mov_b64_e32 v[8:9], 0
	v_mov_b64_e32 v[18:19], 0
	v_mov_b64_e32 v[20:21], 0
	v_mov_b64_e32 v[22:23], 0
	v_mov_b64_e32 v[24:25], 0
	v_mov_b64_e32 v[34:35], 0
	v_mov_b64_e32 v[36:37], 0
	v_mov_b64_e32 v[38:39], 0
	v_mov_b64_e32 v[40:41], 0
	v_mov_b64_e32 v[50:51], 0
	v_mov_b64_e32 v[52:53], 0
	v_mov_b64_e32 v[54:55], 0
	v_mov_b64_e32 v[56:57], 0
	v_mov_b64_e32 v[10:11], 0
	v_mov_b64_e32 v[12:13], 0
	v_mov_b64_e32 v[14:15], 0
	v_mov_b64_e32 v[16:17], 0
	v_mov_b64_e32 v[26:27], 0
	v_mov_b64_e32 v[28:29], 0
	v_mov_b64_e32 v[30:31], 0
	v_mov_b64_e32 v[32:33], 0
	v_mov_b64_e32 v[42:43], 0
	v_mov_b64_e32 v[44:45], 0
	v_mov_b64_e32 v[46:47], 0
	v_mov_b64_e32 v[48:49], 0
	v_mov_b64_e32 v[58:59], 0
	v_mov_b64_e32 v[60:61], 0
	v_mov_b64_e32 v[62:63], 0
	v_mov_b64_e32 v[64:65], 0
	v_mov_b64_e32 v[66:67], 0
	v_mov_b64_e32 v[68:69], 0
	v_mov_b64_e32 v[70:71], 0
	v_mov_b64_e32 v[72:73], 0
	v_mov_b64_e32 v[82:83], 0
	v_mov_b64_e32 v[84:85], 0
	v_mov_b64_e32 v[86:87], 0
	v_mov_b64_e32 v[88:89], 0
	v_mov_b64_e32 v[98:99], 0
	v_mov_b64_e32 v[100:101], 0
	v_mov_b64_e32 v[102:103], 0
	v_mov_b64_e32 v[104:105], 0
	v_mov_b64_e32 v[114:115], 0
	v_mov_b64_e32 v[116:117], 0
	v_mov_b64_e32 v[118:119], 0
	v_mov_b64_e32 v[120:121], 0
	v_mov_b64_e32 v[74:75], 0
	v_mov_b64_e32 v[76:77], 0
	v_mov_b64_e32 v[78:79], 0
	v_mov_b64_e32 v[80:81], 0
	v_mov_b64_e32 v[90:91], 0
	v_mov_b64_e32 v[92:93], 0
	v_mov_b64_e32 v[94:95], 0
	v_mov_b64_e32 v[96:97], 0
	v_mov_b64_e32 v[106:107], 0
	v_mov_b64_e32 v[108:109], 0
	v_mov_b64_e32 v[110:111], 0
	v_mov_b64_e32 v[112:113], 0
	v_mov_b64_e32 v[122:123], 0
	v_mov_b64_e32 v[124:125], 0
	v_mov_b64_e32 v[126:127], 0
	v_mov_b64_e32 v[128:129], 0
	s_cmp_lg_u32 s10, 0
	s_cbranch_scc0 .Lsprio_skip_2
	s_setprio 1

; template <class Epi, bool ALIGN_EPI = true, bool SP2 = true>
; __device__ __forceinline__ void gemm_phase(LAS unsigned char* lds, const Gemm g, const Order& S, const Epi& E) {
;     ...
;         const bool has_next = S.next(ui + 1, nxt);
;         const char* nA = has_next ? (const char*)(nxt.z ? g.A1 : g.A0) + (size_t)nxt.pm * tstepA + (size_t)nxt.kt0 * kstep : cA; const char* nB = has_next ? (const char*)(nxt.z ? g.B1 : g.B0) + (size_t)nxt.pn * tstepB + (size_t)nxt.kt0 * kstep : cB;
;         const int nt = cur.nkt;
;     ...
;         for (int a = 0; a < 2; ++a)
; #pragma unroll
;             for (int b = 0; b < 2; ++b)
; #pragma unroll
;                 for (int m = 0; m < 4; ++m)
; #pragma unroll
;                     for (int n = 0; n < 2; ++n) acc[a][b][m][n] = (f32x4){0.f, 0.f, 0.f, 0.f};
.LBB0_879:
	s_ashr_i32 s85, s84, 31
	s_lshl_b64 s[54:55], s[84:85], 19
	s_add_u32 s11, s50, s54
	s_addc_u32 s35, s51, s55
	s_and_b64 s[54:55], s[88:89], exec
	s_cselect_b32 s87, s35, s13
	s_cselect_b32 s86, s11, s12
	s_ashr_i32 s83, s82, 31
	s_lshl_b64 s[54:55], s[82:83], 19
	s_add_u32 s11, s52, s54
	s_addc_u32 s35, s53, s55
	s_and_b64 s[54:55], s[88:89], exec
	s_cselect_b32 s89, s35, s93
	s_cselect_b32 s88, s11, s92
	s_add_u32 s12, s12, 0x40080
	s_addc_u32 s13, s13, 0
	s_add_u32 s11, s92, 0x100
	v_mov_b32_e32 v2, 0
	s_addc_u32 s35, s93, 0
	s_mov_b32 s54, -2
	v_mov_b32_e32 v3, v2
	v_mov_b64_e32 v[4:5], 0
	v_mov_b64_e32 v[14:15], 0
	v_mov_b64_e32 v[16:17], 0
	v_mov_b64_e32 v[18:19], 0
	v_mov_b64_e32 v[20:21], 0
	v_mov_b64_e32 v[30:31], 0
	v_mov_b64_e32 v[32:33], 0
	v_mov_b64_e32 v[34:35], 0
	v_mov_b64_e32 v[36:37], 0
	v_mov_b64_e32 v[46:47], 0
	v_mov_b64_e32 v[48:49], 0
	v_mov_b64_e32 v[82:83], 0
	v_mov_b64_e32 v[84:85], 0
	v_mov_b64_e32 v[94:95], 0
	v_mov_b64_e32 v[96:97], 0
	v_mov_b64_e32 v[6:7], 0
	v_mov_b64_e32 v[8:9], 0
	v_mov_b64_e32 v[10:11], 0
	v_mov_b64_e32 v[12:13], 0
	v_mov_b64_e32 v[22:23], 0
	v_mov_b64_e32 v[24:25], 0
	v_mov_b64_e32 v[26:27], 0
	v_mov_b64_e32 v[28:29], 0
	v_mov_b64_e32 v[38:39], 0
	v_mov_b64_e32 v[40:41], 0
	v_mov_b64_e32 v[42:43], 0
	v_mov_b64_e32 v[44:45], 0
	v_mov_b64_e32 v[86:87], 0
	v_mov_b64_e32 v[88:89], 0
	v_mov_b64_e32 v[90:91], 0
	v_mov_b64_e32 v[92:93], 0
	v_mov_b64_e32 v[106:107], 0
	v_mov_b64_e32 v[108:109], 0
	v_mov_b64_e32 v[114:115], 0
	v_mov_b64_e32 v[116:117], 0
	v_mov_b64_e32 v[122:123], 0
	v_mov_b64_e32 v[124:125], 0
	v_mov_b64_e32 v[130:131], 0
	v_mov_b64_e32 v[132:133], 0
	v_mov_b64_e32 v[138:139], 0
	v_mov_b64_e32 v[140:141], 0
	v_mov_b64_e32 v[146:147], 0
	v_mov_b64_e32 v[148:149], 0
	v_mov_b64_e32 v[154:155], 0
	v_mov_b64_e32 v[156:157], 0
	v_mov_b64_e32 v[158:159], 0
	v_mov_b64_e32 v[160:161], 0
	v_mov_b64_e32 v[98:99], 0
	v_mov_b64_e32 v[100:101], 0
	v_mov_b64_e32 v[102:103], 0
	v_mov_b64_e32 v[104:105], 0
	v_mov_b64_e32 v[110:111], 0
	v_mov_b64_e32 v[112:113], 0
	v_mov_b64_e32 v[118:119], 0
	v_mov_b64_e32 v[120:121], 0
	v_mov_b64_e32 v[126:127], 0
	v_mov_b64_e32 v[128:129], 0
	v_mov_b64_e32 v[134:135], 0
	v_mov_b64_e32 v[136:137], 0
	v_mov_b64_e32 v[142:143], 0
	v_mov_b64_e32 v[144:145], 0
	v_mov_b64_e32 v[150:151], 0
	v_mov_b64_e32 v[152:153], 0
	s_cmp_lg_u32 s76, 0
	s_cbranch_scc0 .Lsprio_skip_3
	s_setprio 1

; template <class Epi, bool ALIGN_EPI = true, bool SP2 = true>
; __device__ __forceinline__ void gemm_phase(LAS unsigned char* lds, const Gemm g, const Order& S, const Epi& E) {
;     ...
;         const int nt = cur.nkt;
;         for (int t = 0; t < nt; t += 2) {
;             const bool last = (t == nt - 2);
;             const char* a1 = cA + (size_t)(t + 1) * kstep;
;             const char* a2 = last ? nA : cA + (size_t)(t + 2) * kstep; const char* b2 = last ? nB : cB + (size_t)(t + 2) * kstep;
;             const char* a3 = a2 + kstep; const char* b3 = b2 + kstep;
;     ...
;         for (int a = 0; a < 2; ++a)
; #pragma unroll
;             for (int b = 0; b < 2; ++b)
; #pragma unroll
;                 for (int m = 0; m < 4; ++m)
; #pragma unroll
;                     for (int n = 0; n < 2; ++n) acc[a][b][m][n] = (f32x4){0.f, 0.f, 0.f, 0.f};
.LBB0_1096:
	s_add_i32 s13, s55, -2
	s_add_u32 s59, s62, 0x100
	v_mov_b32_e32 v2, 0
	s_addc_u32 s69, s63, 0
	s_mov_b32 s64, 0
	v_mov_b32_e32 v3, v2
	v_mov_b64_e32 v[4:5], 0
	v_mov_b64_e32 v[6:7], 0
	v_mov_b64_e32 v[8:9], 0
	v_mov_b64_e32 v[18:19], 0
	v_mov_b64_e32 v[20:21], 0
	v_mov_b64_e32 v[22:23], 0
	v_mov_b64_e32 v[24:25], 0
	v_mov_b64_e32 v[34:35], 0
	v_mov_b64_e32 v[36:37], 0
	v_mov_b64_e32 v[38:39], 0
	v_mov_b64_e32 v[40:41], 0
	v_mov_b64_e32 v[50:51], 0
	v_mov_b64_e32 v[52:53], 0
	v_mov_b64_e32 v[54:55], 0
	v_mov_b64_e32 v[56:57], 0
	v_mov_b64_e32 v[10:11], 0
	v_mov_b64_e32 v[12:13], 0
	v_mov_b64_e32 v[14:15], 0
	v_mov_b64_e32 v[16:17], 0
	v_mov_b64_e32 v[26:27], 0
	v_mov_b64_e32 v[28:29], 0
	v_mov_b64_e32 v[30:31], 0
	v_mov_b64_e32 v[32:33], 0
	v_mov_b64_e32 v[42:43], 0
	v_mov_b64_e32 v[44:45], 0
	v_mov_b64_e32 v[46:47], 0
	v_mov_b64_e32 v[48:49], 0
	v_mov_b64_e32 v[58:59], 0
	v_mov_b64_e32 v[60:61], 0
	v_mov_b64_e32 v[62:63], 0
	v_mov_b64_e32 v[64:65], 0
	v_mov_b64_e32 v[66:67], 0
	v_mov_b64_e32 v[68:69], 0
	v_mov_b64_e32 v[70:71], 0
	v_mov_b64_e32 v[72:73], 0
	v_mov_b64_e32 v[82:83], 0
	v_mov_b64_e32 v[84:85], 0
	v_mov_b64_e32 v[86:87], 0
	v_mov_b64_e32 v[88:89], 0
	v_mov_b64_e32 v[98:99], 0
	v_mov_b64_e32 v[100:101], 0
	v_mov_b64_e32 v[102:103], 0
	v_mov_b64_e32 v[104:105], 0
	v_mov_b64_e32 v[114:115], 0
	v_mov_b64_e32 v[116:117], 0
	v_mov_b64_e32 v[118:119], 0
	v_mov_b64_e32 v[120:121], 0
	v_mov_b64_e32 v[74:75], 0
	v_mov_b64_e32 v[76:77], 0
	v_mov_b64_e32 v[78:79], 0
	v_mov_b64_e32 v[80:81], 0
	v_mov_b64_e32 v[90:91], 0
	v_mov_b64_e32 v[92:93], 0
	v_mov_b64_e32 v[94:95], 0
	v_mov_b64_e32 v[96:97], 0
	v_mov_b64_e32 v[106:107], 0
	v_mov_b64_e32 v[108:109], 0
	v_mov_b64_e32 v[110:111], 0
	v_mov_b64_e32 v[112:113], 0
	v_mov_b64_e32 v[122:123], 0
	v_mov_b64_e32 v[124:125], 0
	v_mov_b64_e32 v[126:127], 0
	v_mov_b64_e32 v[128:129], 0
	s_cmp_lg_u32 s10, 0
	s_cbranch_scc0 .Lsprio_skip_4
	s_setprio 1
